# MLA fast path: fast-to-fast back edge skips the stage/address recomputation (next tile's V read base computed in the PV phase): -5 SALU -1 VALU per tile
# speedup vs baseline: 1.0094x; 1.0094x over previous
.Lmla_fast_ok:
	v_cvt_pk_bf16_f32 v166, v202, v203
	v_cvt_pk_bf16_f32 v167, v204, v205
	v_cvt_pk_bf16_f32 v168, v206, v207
	v_cvt_pk_bf16_f32 v169, v208, v209
	s_waitcnt lgkmcnt(0)
	s_nop 0
	v_mfma_f32_32x32x16_bf16 v[18:33], v[126:129], v[166:169], v[18:33]
	s_add_i32 s34, s31, 64
	s_cmp_le_u32 s34, s4
	s_cselect_b32 s42, 1, 0
	s_add_i32 s8, s30, 1
	s_and_b32 s8, s8, 3
	s_mulk_i32 s8, 0x6400
	v_add3_u32 v0, s8, v143, v132
	v_add3_u32 v142, s8, v144, v145
	v_mfma_f32_32x32x16_bf16 v[2:17], v[122:125], v[166:169], v[2:17]
	v_cvt_pk_bf16_f32 v170, v210, v211
	v_cvt_pk_bf16_f32 v171, v212, v213
	v_cvt_pk_bf16_f32 v172, v214, v215
	v_cvt_pk_bf16_f32 v173, v216, v217
	v_exp_f32_e32 v218, v34
	v_exp_f32_e32 v219, v35
	v_mfma_f32_32x32x16_bf16 v[18:33], v[118:121], v[170:173], v[18:33]
	v_exp_f32_e32 v220, v36
	v_exp_f32_e32 v221, v37
	ds_read_b128 v[194:197], v0
	ds_read_b128 v[150:153], v0 offset:32
	v_mfma_f32_32x32x16_bf16 v[2:17], v[114:117], v[170:173], v[2:17]
	v_exp_f32_e32 v222, v38
	v_exp_f32_e32 v223, v39
	v_exp_f32_e32 v224, v40
	v_exp_f32_e32 v225, v41
	v_cvt_pk_bf16_f32 v166, v218, v219
	v_cvt_pk_bf16_f32 v167, v220, v221
	v_cvt_pk_bf16_f32 v168, v222, v223
	v_cvt_pk_bf16_f32 v169, v224, v225
	ds_read_b128 v[158:161], v0 offset:64
	ds_read_b128 v[162:165], v0 offset:96
	v_mfma_f32_32x32x16_bf16 v[18:33], v[110:113], v[166:169], v[18:33]
	v_exp_f32_e32 v226, v42
	v_exp_f32_e32 v227, v43
	v_exp_f32_e32 v228, v44
	v_mfma_f32_32x32x16_bf16 v[2:17], v[106:109], v[166:169], v[2:17]
	v_exp_f32_e32 v229, v45
	v_exp_f32_e32 v230, v46
	v_exp_f32_e32 v231, v47
	v_exp_f32_e32 v232, v48
	v_exp_f32_e32 v233, v49
	ds_read_b128 v[174:177], v0 offset:128
	ds_read_b128 v[178:181], v0 offset:160
	v_cvt_pk_bf16_f32 v170, v226, v227
	v_cvt_pk_bf16_f32 v171, v228, v229
	v_cvt_pk_bf16_f32 v172, v230, v231
	v_cvt_pk_bf16_f32 v173, v232, v233
	s_nop 1
	v_mfma_f32_32x32x16_bf16 v[18:33], v[102:105], v[170:173], v[18:33]
	v_mfma_f32_32x32x16_bf16 v[2:17], v[98:101], v[170:173], v[2:17]
	s_add_i32 s30, s30, 1
	s_add_i32 s31, s31, 64
	v_subrev_u32_e32 v146, 64, v146
	s_cmp_lg_u32 s42, 0
	s_cbranch_scc0 .Lmla_fast_generic
	s_not_b64 s[38:39], s[38:39]
	s_not_b64 s[16:17], s[38:39]
	s_branch .Lmla_fast_havek
